# v18 + FFN_DOWN k-loop: LDS store ladder fused with the next-k-tile global loads (each staging group is re-loaded right after its ds_write) so the store path and the load issue overlap
# baseline (speedup 1.0000x reference)
.LBB0_109:
	s_and_saveexec_b64 s[40:41], vcc
	s_xor_b64 s[48:49], exec, s[40:41]
	s_cbranch_execz .LBB0_114
	s_cmp_gt_u32 s61, 41
	s_cbranch_scc1 .Lfl_FFN_DOWN_0_old
	s_andn2_b32 s40, 0x10000, s72
	v_add_u32_e32 v0, s40, v198
	s_waitcnt vmcnt(7)
	ds_write_b128 v0, v[144:147]
	v_lshl_add_u64 v[2:3], v[190:191], 0, s[20:21]
	global_load_dwordx4 v[144:147], v[2:3], off
	s_waitcnt vmcnt(7)
	ds_write_b128 v0, v[148:151] offset:32768
	v_lshl_add_u64 v[2:3], v[182:183], 0, s[20:21]
	global_load_dwordx4 v[148:151], v[2:3], off
	s_waitcnt vmcnt(7)
	ds_write_b128 v0, v[152:155] offset:8192
	v_lshl_add_u64 v[2:3], v[188:189], 0, s[20:21]
	global_load_dwordx4 v[152:155], v[2:3], off
	s_waitcnt vmcnt(7)
	ds_write_b128 v0, v[156:159] offset:40960
	v_lshl_add_u64 v[2:3], v[180:181], 0, s[20:21]
	global_load_dwordx4 v[156:159], v[2:3], off
	s_waitcnt vmcnt(7)
	ds_write_b128 v0, v[160:163] offset:16384
	v_lshl_add_u64 v[2:3], v[186:187], 0, s[20:21]
	global_load_dwordx4 v[160:163], v[2:3], off
	s_waitcnt vmcnt(7)
	ds_write_b128 v0, v[164:167] offset:49152
	v_lshl_add_u64 v[2:3], v[178:179], 0, s[20:21]
	global_load_dwordx4 v[164:167], v[2:3], off
	s_waitcnt vmcnt(7)
	ds_write_b128 v0, v[168:171] offset:24576
	v_lshl_add_u64 v[2:3], v[184:185], 0, s[20:21]
	global_load_dwordx4 v[168:171], v[2:3], off
	s_waitcnt vmcnt(7)
	ds_write_b128 v0, v[172:175] offset:57344
	v_lshl_add_u64 v[2:3], v[176:177], 0, s[20:21]
	global_load_dwordx4 v[172:175], v[2:3], off
	s_branch .Lfl_FFN_DOWN_0_done
.Lfl_FFN_DOWN_0_old:
	s_cmp_gt_u32 s61, 42
	s_cbranch_scc1 .LBB0_112
	s_andn2_b32 s40, 0x10000, s72
	v_add_u32_e32 v0, s40, v198
	s_waitcnt vmcnt(7)
	ds_write_b128 v0, v[144:147]
	s_waitcnt vmcnt(6)
	ds_write_b128 v0, v[148:151] offset:32768
	s_waitcnt vmcnt(5)
	ds_write_b128 v0, v[152:155] offset:8192
	s_waitcnt vmcnt(4)
	ds_write_b128 v0, v[156:159] offset:40960
	s_waitcnt vmcnt(3)
	ds_write_b128 v0, v[160:163] offset:16384
	s_waitcnt vmcnt(2)
	ds_write_b128 v0, v[164:167] offset:49152
	s_waitcnt vmcnt(1)
	ds_write_b128 v0, v[168:171] offset:24576
	s_waitcnt vmcnt(0)
	ds_write_b128 v0, v[172:175] offset:57344

.Lfl_FFN_DOWN_0_done:
.LBB0_114:
	s_andn2_saveexec_b64 s[48:49], s[48:49]
	s_cbranch_execz .LBB0_116
	s_and_b32 s40, s72, 0x10000
	v_add_u32_e32 v0, s40, v192
	v_or_b32_e32 v2, s40, v193
	v_add_u32_e32 v14, v0, v194
	v_add_u32_e32 v15, v0, v195
	v_add_u32_e32 v199, v0, v196
	v_add_u32_e32 v0, v0, v197
	v_add_u32_e32 v205, v2, v194
	v_add_u32_e32 v228, v2, v195
	v_add_u32_e32 v250, v2, v196
	v_add_u32_e32 v251, v2, v197
	s_setprio 1
	ds_read_b128 v[2:5], v14 offset:0
	ds_read_b128 v[6:9], v14 offset:4096
	ds_read_b128 v[10:13], v14 offset:8192
	ds_read_b128 v[208:211], v14 offset:12288
	ds_read_b128 v[242:245], v205 offset:0
	ds_read_b128 v[246:249], v205 offset:4096
	ds_read_b128 v[214:217], v15 offset:0
	ds_read_b128 v[230:233], v15 offset:4096
	ds_read_b128 v[234:237], v15 offset:8192
	ds_read_b128 v[238:241], v15 offset:12288
	s_waitcnt lgkmcnt(4)
	v_mfma_f32_32x32x16_bf16 v[128:143], v[2:5], v[242:245], v[128:143]
	v_mfma_f32_32x32x16_bf16 v[96:111], v[6:9], v[242:245], v[96:111]
	v_mfma_f32_32x32x16_bf16 v[64:79], v[10:13], v[242:245], v[64:79]
	v_mfma_f32_32x32x16_bf16 v[32:47], v[208:211], v[242:245], v[32:47]
	ds_read_b128 v[242:245], v228 offset:0
	v_mfma_f32_32x32x16_bf16 v[112:127], v[2:5], v[246:249], v[112:127]
	v_mfma_f32_32x32x16_bf16 v[80:95], v[6:9], v[246:249], v[80:95]
	v_mfma_f32_32x32x16_bf16 v[48:63], v[10:13], v[246:249], v[48:63]
	v_mfma_f32_32x32x16_bf16 v[16:31], v[208:211], v[246:249], v[16:31]
	ds_read_b128 v[246:249], v228 offset:4096
	ds_read_b128 v[2:5], v199 offset:0
	ds_read_b128 v[6:9], v199 offset:4096
	ds_read_b128 v[10:13], v199 offset:8192
	ds_read_b128 v[208:211], v199 offset:12288
	s_waitcnt lgkmcnt(5)
	v_mfma_f32_32x32x16_bf16 v[128:143], v[214:217], v[242:245], v[128:143]
	v_mfma_f32_32x32x16_bf16 v[96:111], v[230:233], v[242:245], v[96:111]
	v_mfma_f32_32x32x16_bf16 v[64:79], v[234:237], v[242:245], v[64:79]
	v_mfma_f32_32x32x16_bf16 v[32:47], v[238:241], v[242:245], v[32:47]
	ds_read_b128 v[242:245], v250 offset:0
	s_waitcnt lgkmcnt(5)
	v_mfma_f32_32x32x16_bf16 v[112:127], v[214:217], v[246:249], v[112:127]
	v_mfma_f32_32x32x16_bf16 v[80:95], v[230:233], v[246:249], v[80:95]
	v_mfma_f32_32x32x16_bf16 v[48:63], v[234:237], v[246:249], v[48:63]
	v_mfma_f32_32x32x16_bf16 v[16:31], v[238:241], v[246:249], v[16:31]
	ds_read_b128 v[246:249], v250 offset:4096
	ds_read_b128 v[214:217], v0 offset:0
	ds_read_b128 v[230:233], v0 offset:4096
	ds_read_b128 v[234:237], v0 offset:8192
	ds_read_b128 v[238:241], v0 offset:12288
	s_waitcnt lgkmcnt(5)
	v_mfma_f32_32x32x16_bf16 v[128:143], v[2:5], v[242:245], v[128:143]
	v_mfma_f32_32x32x16_bf16 v[96:111], v[6:9], v[242:245], v[96:111]
	v_mfma_f32_32x32x16_bf16 v[64:79], v[10:13], v[242:245], v[64:79]
	v_mfma_f32_32x32x16_bf16 v[32:47], v[208:211], v[242:245], v[32:47]
	ds_read_b128 v[242:245], v251 offset:0
	s_waitcnt lgkmcnt(5)
	v_mfma_f32_32x32x16_bf16 v[112:127], v[2:5], v[246:249], v[112:127]
	v_mfma_f32_32x32x16_bf16 v[80:95], v[6:9], v[246:249], v[80:95]
	v_mfma_f32_32x32x16_bf16 v[48:63], v[10:13], v[246:249], v[48:63]
	v_mfma_f32_32x32x16_bf16 v[16:31], v[208:211], v[246:249], v[16:31]
	ds_read_b128 v[246:249], v251 offset:4096
	s_waitcnt lgkmcnt(1)
	v_mfma_f32_32x32x16_bf16 v[128:143], v[214:217], v[242:245], v[128:143]
	v_mfma_f32_32x32x16_bf16 v[96:111], v[230:233], v[242:245], v[96:111]
	v_mfma_f32_32x32x16_bf16 v[64:79], v[234:237], v[242:245], v[64:79]
	v_mfma_f32_32x32x16_bf16 v[32:47], v[238:241], v[242:245], v[32:47]
	s_waitcnt lgkmcnt(0)
	v_mfma_f32_32x32x16_bf16 v[112:127], v[214:217], v[246:249], v[112:127]
	v_mfma_f32_32x32x16_bf16 v[80:95], v[230:233], v[246:249], v[80:95]
	v_mfma_f32_32x32x16_bf16 v[48:63], v[234:237], v[246:249], v[48:63]
	v_mfma_f32_32x32x16_bf16 v[16:31], v[238:241], v[246:249], v[16:31]
	s_nop 15
	s_nop 7

	s_setprio 0
.LBB0_116:
	s_or_b64 exec, exec, s[48:49]
	s_and_saveexec_b64 s[40:41], s[46:47]
	s_xor_b64 s[48:49], exec, s[40:41]
	s_cbranch_execz .LBB0_121
	s_cmp_gt_u32 s61, 41
	s_cbranch_scc1 .Lfl_FFN_DOWN_1_old
	s_add_i32 s40, s72, 0x10000
	s_and_b32 s40, s40, 0x10000
	v_add_u32_e32 v0, s40, v198
	s_waitcnt vmcnt(7)
	ds_write_b128 v0, v[144:147]
	v_lshl_add_u64 v[2:3], v[190:191], 0, s[20:21]
	global_load_dwordx4 v[144:147], v[2:3], off
	s_waitcnt vmcnt(7)
	ds_write_b128 v0, v[148:151] offset:32768
	v_lshl_add_u64 v[2:3], v[182:183], 0, s[20:21]
	global_load_dwordx4 v[148:151], v[2:3], off
	s_waitcnt vmcnt(7)
	ds_write_b128 v0, v[152:155] offset:8192
	v_lshl_add_u64 v[2:3], v[188:189], 0, s[20:21]
	global_load_dwordx4 v[152:155], v[2:3], off
	s_waitcnt vmcnt(7)
	ds_write_b128 v0, v[156:159] offset:40960
	v_lshl_add_u64 v[2:3], v[180:181], 0, s[20:21]
	global_load_dwordx4 v[156:159], v[2:3], off
	s_waitcnt vmcnt(7)
	ds_write_b128 v0, v[160:163] offset:16384
	v_lshl_add_u64 v[2:3], v[186:187], 0, s[20:21]
	global_load_dwordx4 v[160:163], v[2:3], off
	s_waitcnt vmcnt(7)
	ds_write_b128 v0, v[164:167] offset:49152
	v_lshl_add_u64 v[2:3], v[178:179], 0, s[20:21]
	global_load_dwordx4 v[164:167], v[2:3], off
	s_waitcnt vmcnt(7)
	ds_write_b128 v0, v[168:171] offset:24576
	v_lshl_add_u64 v[2:3], v[184:185], 0, s[20:21]
	global_load_dwordx4 v[168:171], v[2:3], off
	s_waitcnt vmcnt(7)
	ds_write_b128 v0, v[172:175] offset:57344
	v_lshl_add_u64 v[2:3], v[176:177], 0, s[20:21]
	global_load_dwordx4 v[172:175], v[2:3], off
	s_branch .Lfl_FFN_DOWN_1_done
.Lfl_FFN_DOWN_1_old:
	s_cmp_gt_u32 s61, 42
	s_cbranch_scc1 .LBB0_119
	s_add_i32 s40, s72, 0x10000
	s_and_b32 s40, s40, 0x10000
	v_add_u32_e32 v0, s40, v198
	s_waitcnt vmcnt(7)
	ds_write_b128 v0, v[144:147]
	s_waitcnt vmcnt(6)
	ds_write_b128 v0, v[148:151] offset:32768
	s_waitcnt vmcnt(5)
	ds_write_b128 v0, v[152:155] offset:8192
	s_waitcnt vmcnt(4)
	ds_write_b128 v0, v[156:159] offset:40960
	s_waitcnt vmcnt(3)
	ds_write_b128 v0, v[160:163] offset:16384
	s_waitcnt vmcnt(2)
	ds_write_b128 v0, v[164:167] offset:49152
	s_waitcnt vmcnt(1)
	ds_write_b128 v0, v[168:171] offset:24576
	s_waitcnt vmcnt(0)
	ds_write_b128 v0, v[172:175] offset:57344

.Lfl_FFN_DOWN_1_done:
.LBB0_121:
	s_andn2_saveexec_b64 s[48:49], s[48:49]
	s_cbranch_execz .LBB0_108
	s_and_b32 s40, s72, 0x10000
	v_add_u32_e32 v0, s40, v192
	v_or_b32_e32 v2, s40, v193
	v_add_u32_e32 v14, v0, v194
	v_add_u32_e32 v15, v0, v195
	v_add_u32_e32 v199, v0, v196
	v_add_u32_e32 v0, v0, v197
	v_add_u32_e32 v205, v2, v194
	v_add_u32_e32 v228, v2, v195
	v_add_u32_e32 v250, v2, v196
	v_add_u32_e32 v251, v2, v197
	s_setprio 1
	ds_read_b128 v[2:5], v14 offset:0
	ds_read_b128 v[6:9], v14 offset:4096
	ds_read_b128 v[10:13], v14 offset:8192
	ds_read_b128 v[208:211], v14 offset:12288
	ds_read_b128 v[242:245], v205 offset:0
	ds_read_b128 v[246:249], v205 offset:4096
	ds_read_b128 v[214:217], v15 offset:0
	ds_read_b128 v[230:233], v15 offset:4096
	ds_read_b128 v[234:237], v15 offset:8192
	ds_read_b128 v[238:241], v15 offset:12288
	s_waitcnt lgkmcnt(4)
	v_mfma_f32_32x32x16_bf16 v[128:143], v[2:5], v[242:245], v[128:143]
	v_mfma_f32_32x32x16_bf16 v[96:111], v[6:9], v[242:245], v[96:111]
	v_mfma_f32_32x32x16_bf16 v[64:79], v[10:13], v[242:245], v[64:79]
	v_mfma_f32_32x32x16_bf16 v[32:47], v[208:211], v[242:245], v[32:47]
	ds_read_b128 v[242:245], v228 offset:0
	v_mfma_f32_32x32x16_bf16 v[112:127], v[2:5], v[246:249], v[112:127]
	v_mfma_f32_32x32x16_bf16 v[80:95], v[6:9], v[246:249], v[80:95]
	v_mfma_f32_32x32x16_bf16 v[48:63], v[10:13], v[246:249], v[48:63]
	v_mfma_f32_32x32x16_bf16 v[16:31], v[208:211], v[246:249], v[16:31]
	ds_read_b128 v[246:249], v228 offset:4096
	ds_read_b128 v[2:5], v199 offset:0
	ds_read_b128 v[6:9], v199 offset:4096
	ds_read_b128 v[10:13], v199 offset:8192
	ds_read_b128 v[208:211], v199 offset:12288
	s_waitcnt lgkmcnt(5)
	v_mfma_f32_32x32x16_bf16 v[128:143], v[214:217], v[242:245], v[128:143]
	v_mfma_f32_32x32x16_bf16 v[96:111], v[230:233], v[242:245], v[96:111]
	v_mfma_f32_32x32x16_bf16 v[64:79], v[234:237], v[242:245], v[64:79]
	v_mfma_f32_32x32x16_bf16 v[32:47], v[238:241], v[242:245], v[32:47]
	ds_read_b128 v[242:245], v250 offset:0
	s_waitcnt lgkmcnt(5)
	v_mfma_f32_32x32x16_bf16 v[112:127], v[214:217], v[246:249], v[112:127]
	v_mfma_f32_32x32x16_bf16 v[80:95], v[230:233], v[246:249], v[80:95]
	v_mfma_f32_32x32x16_bf16 v[48:63], v[234:237], v[246:249], v[48:63]
	v_mfma_f32_32x32x16_bf16 v[16:31], v[238:241], v[246:249], v[16:31]
	ds_read_b128 v[246:249], v250 offset:4096
	ds_read_b128 v[214:217], v0 offset:0
	ds_read_b128 v[230:233], v0 offset:4096
	ds_read_b128 v[234:237], v0 offset:8192
	ds_read_b128 v[238:241], v0 offset:12288
	s_waitcnt lgkmcnt(5)
	v_mfma_f32_32x32x16_bf16 v[128:143], v[2:5], v[242:245], v[128:143]
	v_mfma_f32_32x32x16_bf16 v[96:111], v[6:9], v[242:245], v[96:111]
	v_mfma_f32_32x32x16_bf16 v[64:79], v[10:13], v[242:245], v[64:79]
	v_mfma_f32_32x32x16_bf16 v[32:47], v[208:211], v[242:245], v[32:47]
	ds_read_b128 v[242:245], v251 offset:0
	s_waitcnt lgkmcnt(5)
	v_mfma_f32_32x32x16_bf16 v[112:127], v[2:5], v[246:249], v[112:127]
	v_mfma_f32_32x32x16_bf16 v[80:95], v[6:9], v[246:249], v[80:95]
	v_mfma_f32_32x32x16_bf16 v[48:63], v[10:13], v[246:249], v[48:63]
	v_mfma_f32_32x32x16_bf16 v[16:31], v[208:211], v[246:249], v[16:31]
	ds_read_b128 v[246:249], v251 offset:4096
	s_waitcnt lgkmcnt(1)
	v_mfma_f32_32x32x16_bf16 v[128:143], v[214:217], v[242:245], v[128:143]
	v_mfma_f32_32x32x16_bf16 v[96:111], v[230:233], v[242:245], v[96:111]
	v_mfma_f32_32x32x16_bf16 v[64:79], v[234:237], v[242:245], v[64:79]
	v_mfma_f32_32x32x16_bf16 v[32:47], v[238:241], v[242:245], v[32:47]
	s_waitcnt lgkmcnt(0)
	v_mfma_f32_32x32x16_bf16 v[112:127], v[214:217], v[246:249], v[112:127]
	v_mfma_f32_32x32x16_bf16 v[80:95], v[230:233], v[246:249], v[80:95]
	v_mfma_f32_32x32x16_bf16 v[48:63], v[234:237], v[246:249], v[48:63]
	v_mfma_f32_32x32x16_bf16 v[16:31], v[238:241], v[246:249], v[16:31]
	s_nop 15
	s_nop 7

	s_setprio 0
	s_branch .LBB0_108
